# P7 residual epilogue: same 3-block load ring as P5 (8 HBM round trips per tile removed); plus P5 ring and P6 batched row-sum loads
# baseline (speedup 1.0000x reference)
; __device__ __forceinline__ unsigned cvt_pk_bf16(float lo, float hi) { unsigned r; asm volatile("v_cvt_pk_bf16_f32 %0, %1, %2" : "=v"(r) : "v"(lo), "v"(hi)); return r; }
;     __device__ __forceinline__ void operator()(const f32x4 (&acc)[2][2][4][2], const Unit& u, int wr, int wc, int fr, int fq) const {
;         const int row0 = u.pm * BM + wr * 64 + fr, col0 = u.pn * BM + wc * 32 + 4 * fq;
; #pragma unroll
;         for (int ai = 0; ai < 2; ++ai)
; #pragma unroll
;             for (int m = 0; m < 4; ++m) { const int row = row0 + ai * HALF + m * 16; const size_t ro = (size_t)row * 2048 + col0; float ss = 0.f;
; #pragma unroll
;                 for (int bj = 0; bj < 2; ++bj)
; #pragma unroll
;                     for (int n = 0; n < 2; ++n) { const size_t off = ro + bj * HALF + n * 16; const f32x4 hv = *(const f32x4*)(R + off) + acc[ai][bj][m][n];
;                         *(f32x4*)(H + off) = hv; ss += (hv[0] * hv[0] + hv[1] * hv[1]) + (hv[2] * hv[2] + hv[3] * hv[3]);
;                         if (WITH_A5) { const f32x4 gv = *(const f32x4*)(gm + col0 + bj * HALF + n * 16); u32x2 w; w.x = cvt_pk_bf16(hv[0] * gv[0], hv[1] * gv[1]); w.y = cvt_pk_bf16(hv[2] * gv[2], hv[3] * gv[3]); *(u32x2*)(a5 + off) = w; } }
;                 ss += __shfl_xor(ss, 16); ss += __shfl_xor(ss, 32);
;                 if (fq == 0) atomicAdd(rowss + row, ss); }
.LBB0_904:
	v_lshlrev_b32_e32 v222, 13, v144
	v_lshl_add_u32 v222, v146, 2, v222
	v_lshlrev_b32_e32 v153, 2, v144
	v_xor_b32_e32 v151, 16, v150
	v_xor_b32_e32 v152, 32, v150
	v_lshlrev_b32_e32 v151, 2, v151
	v_lshlrev_b32_e32 v152, 2, v152
	s_lshl_b32 s62, s22, 21
	s_lshl_b32 s63, s24, 10
	s_add_u32 s62, s62, s63
	s_add_u32 s52, s86, s62
	s_addc_u32 s53, s87, 0
	s_add_u32 s54, s86, s62
	s_addc_u32 s55, s87, 0
	s_lshl_b32 s63, s22, 10
	s_add_u32 s58, s10, s63
	s_addc_u32 s59, s11, 0
	global_load_dwordx4 v[174:177], v222, s[52:53]
	global_load_dwordx4 v[178:181], v222, s[52:53] offset:64
	global_load_dwordx4 v[182:185], v222, s[52:53] offset:512
	global_load_dwordx4 v[186:189], v222, s[52:53] offset:576
	s_add_u32 s52, s52, 0x20000
	s_addc_u32 s53, s53, 0
	global_load_dwordx4 v[190:193], v222, s[52:53]
	global_load_dwordx4 v[194:197], v222, s[52:53] offset:64
	global_load_dwordx4 v[198:201], v222, s[52:53] offset:512
	global_load_dwordx4 v[202:205], v222, s[52:53] offset:576
	s_add_u32 s52, s52, 0x20000
	s_addc_u32 s53, s53, 0
	global_load_dwordx4 v[206:209], v222, s[52:53]
	global_load_dwordx4 v[210:213], v222, s[52:53] offset:64
	global_load_dwordx4 v[214:217], v222, s[52:53] offset:512
	global_load_dwordx4 v[218:221], v222, s[52:53] offset:576
	s_add_u32 s52, s52, 0x20000
	s_addc_u32 s53, s53, 0
	s_waitcnt vmcnt(8)
	v_pk_add_f32 v[124:125], v[124:125], v[174:175]
	v_pk_add_f32 v[126:127], v[126:127], v[176:177]
	v_pk_add_f32 v[120:121], v[120:121], v[178:179]
	v_pk_add_f32 v[122:123], v[122:123], v[180:181]
	v_pk_add_f32 v[116:117], v[116:117], v[182:183]
	v_pk_add_f32 v[118:119], v[118:119], v[184:185]
	v_pk_add_f32 v[112:113], v[112:113], v[186:187]
	v_pk_add_f32 v[114:115], v[114:115], v[188:189]
	global_load_dwordx4 v[174:177], v222, s[52:53]
	global_load_dwordx4 v[178:181], v222, s[52:53] offset:64
	global_load_dwordx4 v[182:185], v222, s[52:53] offset:512
	global_load_dwordx4 v[186:189], v222, s[52:53] offset:576
	s_add_u32 s52, s52, 0xa0000
	s_addc_u32 s53, s53, 0
	global_store_dwordx4 v222, v[124:127], s[54:55]
	global_store_dwordx4 v222, v[120:123], s[54:55] offset:64
	global_store_dwordx4 v222, v[116:119], s[54:55] offset:512
	global_store_dwordx4 v222, v[112:115], s[54:55] offset:576
	s_add_u32 s54, s54, 0x20000
	s_addc_u32 s55, s55, 0
	v_mul_f32_e32 v140, v125, v125
	v_mul_f32_e32 v141, v127, v127
	v_fmac_f32_e32 v140, v124, v124
	v_fmac_f32_e32 v141, v126, v126
	v_add_f32_e32 v142, v140, v141
	v_mul_f32_e32 v140, v121, v121
	v_mul_f32_e32 v141, v123, v123
	v_fmac_f32_e32 v140, v120, v120
	v_fmac_f32_e32 v141, v122, v122
	v_add_f32_e32 v140, v140, v141
	v_add_f32_e32 v142, v142, v140
	v_mul_f32_e32 v140, v117, v117
	v_mul_f32_e32 v141, v119, v119
	v_fmac_f32_e32 v140, v116, v116
	v_fmac_f32_e32 v141, v118, v118
	v_add_f32_e32 v140, v140, v141
	v_add_f32_e32 v142, v142, v140
	v_mul_f32_e32 v140, v113, v113
	v_mul_f32_e32 v141, v115, v115
	v_fmac_f32_e32 v140, v112, v112
	v_fmac_f32_e32 v141, v114, v114
	v_add_f32_e32 v140, v140, v141
	v_add_f32_e32 v142, v142, v140
	v_mov_b32_e32 v112, v142
	s_waitcnt vmcnt(12)
	v_pk_add_f32 v[108:109], v[108:109], v[190:191]
	v_pk_add_f32 v[110:111], v[110:111], v[192:193]
	v_pk_add_f32 v[104:105], v[104:105], v[194:195]
	v_pk_add_f32 v[106:107], v[106:107], v[196:197]
	v_pk_add_f32 v[100:101], v[100:101], v[198:199]
	v_pk_add_f32 v[102:103], v[102:103], v[200:201]
	v_pk_add_f32 v[96:97], v[96:97], v[202:203]
	v_pk_add_f32 v[98:99], v[98:99], v[204:205]
	global_load_dwordx4 v[190:193], v222, s[52:53]
	global_load_dwordx4 v[194:197], v222, s[52:53] offset:64
	global_load_dwordx4 v[198:201], v222, s[52:53] offset:512
	global_load_dwordx4 v[202:205], v222, s[52:53] offset:576
	s_add_u32 s52, s52, 0x20000
	s_addc_u32 s53, s53, 0
	global_store_dwordx4 v222, v[108:111], s[54:55]
	global_store_dwordx4 v222, v[104:107], s[54:55] offset:64
	global_store_dwordx4 v222, v[100:103], s[54:55] offset:512
	global_store_dwordx4 v222, v[96:99], s[54:55] offset:576
	s_add_u32 s54, s54, 0x20000
	s_addc_u32 s55, s55, 0
	v_mul_f32_e32 v140, v109, v109
	v_mul_f32_e32 v141, v111, v111
	v_fmac_f32_e32 v140, v108, v108
	v_fmac_f32_e32 v141, v110, v110
	v_add_f32_e32 v142, v140, v141
	v_mul_f32_e32 v140, v105, v105
	v_mul_f32_e32 v141, v107, v107
	v_fmac_f32_e32 v140, v104, v104
	v_fmac_f32_e32 v141, v106, v106
	v_add_f32_e32 v140, v140, v141
	v_add_f32_e32 v142, v142, v140
	v_mul_f32_e32 v140, v101, v101
	v_mul_f32_e32 v141, v103, v103
	v_fmac_f32_e32 v140, v100, v100
	v_fmac_f32_e32 v141, v102, v102
	v_add_f32_e32 v140, v140, v141
	v_add_f32_e32 v142, v142, v140
	v_mul_f32_e32 v140, v97, v97
	v_mul_f32_e32 v141, v99, v99
	v_fmac_f32_e32 v140, v96, v96
	v_fmac_f32_e32 v141, v98, v98
	v_add_f32_e32 v140, v140, v141
	v_add_f32_e32 v142, v142, v140
	v_mov_b32_e32 v96, v142
	s_waitcnt vmcnt(16)
	v_pk_add_f32 v[92:93], v[92:93], v[206:207]
	v_pk_add_f32 v[94:95], v[94:95], v[208:209]
	v_pk_add_f32 v[88:89], v[88:89], v[210:211]
	v_pk_add_f32 v[90:91], v[90:91], v[212:213]
	v_pk_add_f32 v[84:85], v[84:85], v[214:215]
	v_pk_add_f32 v[86:87], v[86:87], v[216:217]
	v_pk_add_f32 v[80:81], v[80:81], v[218:219]
	v_pk_add_f32 v[82:83], v[82:83], v[220:221]
	global_load_dwordx4 v[206:209], v222, s[52:53]
	global_load_dwordx4 v[210:213], v222, s[52:53] offset:64
	global_load_dwordx4 v[214:217], v222, s[52:53] offset:512
	global_load_dwordx4 v[218:221], v222, s[52:53] offset:576
	s_add_u32 s52, s52, 0x20000
	s_addc_u32 s53, s53, 0
	global_store_dwordx4 v222, v[92:95], s[54:55]
	global_store_dwordx4 v222, v[88:91], s[54:55] offset:64
	global_store_dwordx4 v222, v[84:87], s[54:55] offset:512
	global_store_dwordx4 v222, v[80:83], s[54:55] offset:576
	s_add_u32 s54, s54, 0x20000
	s_addc_u32 s55, s55, 0
	v_mul_f32_e32 v140, v93, v93
	v_mul_f32_e32 v141, v95, v95
	v_fmac_f32_e32 v140, v92, v92
	v_fmac_f32_e32 v141, v94, v94
	v_add_f32_e32 v142, v140, v141
	v_mul_f32_e32 v140, v89, v89
	v_mul_f32_e32 v141, v91, v91
	v_fmac_f32_e32 v140, v88, v88
	v_fmac_f32_e32 v141, v90, v90
	v_add_f32_e32 v140, v140, v141
	v_add_f32_e32 v142, v142, v140
	v_mul_f32_e32 v140, v85, v85
	v_mul_f32_e32 v141, v87, v87
	v_fmac_f32_e32 v140, v84, v84
	v_fmac_f32_e32 v141, v86, v86
	v_add_f32_e32 v140, v140, v141
	v_add_f32_e32 v142, v142, v140
	v_mul_f32_e32 v140, v81, v81
	v_mul_f32_e32 v141, v83, v83
	v_fmac_f32_e32 v140, v80, v80
	v_fmac_f32_e32 v141, v82, v82
	v_add_f32_e32 v140, v140, v141
	v_add_f32_e32 v142, v142, v140
	v_mov_b32_e32 v80, v142
	s_waitcnt vmcnt(20)
;     __device__ __forceinline__ void operator()(const f32x4 (&acc)[2][2][4][2], const Unit& u, int wr, int wc, int fr, int fq) const {
;     ...
;             for (int m = 0; m < 4; ++m) { const int row = row0 + ai * HALF + m * 16; const size_t ro = (size_t)row * 2048 + col0; float ss = 0.f;
; #pragma unroll
;                 for (int bj = 0; bj < 2; ++bj)
; #pragma unroll
;                     for (int n = 0; n < 2; ++n) { const size_t off = ro + bj * HALF + n * 16; const f32x4 hv = *(const f32x4*)(R + off) + acc[ai][bj][m][n];
;                         *(f32x4*)(H + off) = hv; ss += (hv[0] * hv[0] + hv[1] * hv[1]) + (hv[2] * hv[2] + hv[3] * hv[3]);
	v_pk_add_f32 v[76:77], v[76:77], v[174:175]
	v_pk_add_f32 v[78:79], v[78:79], v[176:177]
	v_pk_add_f32 v[72:73], v[72:73], v[178:179]
	v_pk_add_f32 v[74:75], v[74:75], v[180:181]
	v_pk_add_f32 v[68:69], v[68:69], v[182:183]
	v_pk_add_f32 v[70:71], v[70:71], v[184:185]
	v_pk_add_f32 v[64:65], v[64:65], v[186:187]
	v_pk_add_f32 v[66:67], v[66:67], v[188:189]
	global_load_dwordx4 v[174:177], v222, s[52:53]
	global_load_dwordx4 v[178:181], v222, s[52:53] offset:64
	global_load_dwordx4 v[182:185], v222, s[52:53] offset:512
	global_load_dwordx4 v[186:189], v222, s[52:53] offset:576
	s_add_u32 s52, s52, 0x20000
	s_addc_u32 s53, s53, 0
	global_store_dwordx4 v222, v[76:79], s[54:55]
	global_store_dwordx4 v222, v[72:75], s[54:55] offset:64
	global_store_dwordx4 v222, v[68:71], s[54:55] offset:512
	global_store_dwordx4 v222, v[64:67], s[54:55] offset:576
	s_add_u32 s54, s54, 0xa0000
	s_addc_u32 s55, s55, 0
	v_mul_f32_e32 v140, v77, v77
	v_mul_f32_e32 v141, v79, v79
	v_fmac_f32_e32 v140, v76, v76
	v_fmac_f32_e32 v141, v78, v78
	v_add_f32_e32 v142, v140, v141
	v_mul_f32_e32 v140, v73, v73
	v_mul_f32_e32 v141, v75, v75
	v_fmac_f32_e32 v140, v72, v72
	v_fmac_f32_e32 v141, v74, v74
	v_add_f32_e32 v140, v140, v141
	v_add_f32_e32 v142, v142, v140
	v_mul_f32_e32 v140, v69, v69
	v_mul_f32_e32 v141, v71, v71
	v_fmac_f32_e32 v140, v68, v68
	v_fmac_f32_e32 v141, v70, v70
	v_add_f32_e32 v140, v140, v141
	v_add_f32_e32 v142, v142, v140
	v_mul_f32_e32 v140, v65, v65
	v_mul_f32_e32 v141, v67, v67
	v_fmac_f32_e32 v140, v64, v64
	v_fmac_f32_e32 v141, v66, v66
	v_add_f32_e32 v140, v140, v141
	v_add_f32_e32 v142, v142, v140
	v_mov_b32_e32 v64, v142
	s_waitcnt vmcnt(20)
	v_pk_add_f32 v[60:61], v[60:61], v[190:191]
	v_pk_add_f32 v[62:63], v[62:63], v[192:193]
	v_pk_add_f32 v[56:57], v[56:57], v[194:195]
	v_pk_add_f32 v[58:59], v[58:59], v[196:197]
	v_pk_add_f32 v[52:53], v[52:53], v[198:199]
	v_pk_add_f32 v[54:55], v[54:55], v[200:201]
	v_pk_add_f32 v[48:49], v[48:49], v[202:203]
	v_pk_add_f32 v[50:51], v[50:51], v[204:205]
	global_load_dwordx4 v[190:193], v222, s[52:53]
	global_load_dwordx4 v[194:197], v222, s[52:53] offset:64
	global_load_dwordx4 v[198:201], v222, s[52:53] offset:512
	global_load_dwordx4 v[202:205], v222, s[52:53] offset:576
	global_store_dwordx4 v222, v[60:63], s[54:55]
	global_store_dwordx4 v222, v[56:59], s[54:55] offset:64
	global_store_dwordx4 v222, v[52:55], s[54:55] offset:512
	global_store_dwordx4 v222, v[48:51], s[54:55] offset:576
	s_add_u32 s54, s54, 0x20000
	s_addc_u32 s55, s55, 0
	v_mul_f32_e32 v140, v61, v61
	v_mul_f32_e32 v141, v63, v63
	v_fmac_f32_e32 v140, v60, v60
	v_fmac_f32_e32 v141, v62, v62
	v_add_f32_e32 v142, v140, v141
	v_mul_f32_e32 v140, v57, v57
	v_mul_f32_e32 v141, v59, v59
	v_fmac_f32_e32 v140, v56, v56
	v_fmac_f32_e32 v141, v58, v58
	v_add_f32_e32 v140, v140, v141
	v_add_f32_e32 v142, v142, v140
	v_mul_f32_e32 v140, v53, v53
	v_mul_f32_e32 v141, v55, v55
	v_fmac_f32_e32 v140, v52, v52
	v_fmac_f32_e32 v141, v54, v54
	v_add_f32_e32 v140, v140, v141
	v_add_f32_e32 v142, v142, v140
	v_mul_f32_e32 v140, v49, v49
	v_mul_f32_e32 v141, v51, v51
	v_fmac_f32_e32 v140, v48, v48
	v_fmac_f32_e32 v141, v50, v50
	v_add_f32_e32 v140, v140, v141
	v_add_f32_e32 v142, v142, v140
	v_mov_b32_e32 v48, v142
	s_waitcnt vmcnt(20)
	v_pk_add_f32 v[44:45], v[44:45], v[206:207]
	v_pk_add_f32 v[46:47], v[46:47], v[208:209]
	v_pk_add_f32 v[40:41], v[40:41], v[210:211]
	v_pk_add_f32 v[42:43], v[42:43], v[212:213]
	v_pk_add_f32 v[36:37], v[36:37], v[214:215]
	v_pk_add_f32 v[38:39], v[38:39], v[216:217]
	v_pk_add_f32 v[32:33], v[32:33], v[218:219]
	v_pk_add_f32 v[34:35], v[34:35], v[220:221]
	global_store_dwordx4 v222, v[44:47], s[54:55]
	global_store_dwordx4 v222, v[40:43], s[54:55] offset:64
	global_store_dwordx4 v222, v[36:39], s[54:55] offset:512
	global_store_dwordx4 v222, v[32:35], s[54:55] offset:576
	s_add_u32 s54, s54, 0x20000
	s_addc_u32 s55, s55, 0
	v_mul_f32_e32 v140, v45, v45
	v_mul_f32_e32 v141, v47, v47
	v_fmac_f32_e32 v140, v44, v44
	v_fmac_f32_e32 v141, v46, v46
	v_add_f32_e32 v142, v140, v141
	v_mul_f32_e32 v140, v41, v41
	v_mul_f32_e32 v141, v43, v43
	v_fmac_f32_e32 v140, v40, v40
	v_fmac_f32_e32 v141, v42, v42
	v_add_f32_e32 v140, v140, v141
	v_add_f32_e32 v142, v142, v140
	v_mul_f32_e32 v140, v37, v37
	v_mul_f32_e32 v141, v39, v39
	v_fmac_f32_e32 v140, v36, v36
	v_fmac_f32_e32 v141, v38, v38
	v_add_f32_e32 v140, v140, v141
	v_add_f32_e32 v142, v142, v140
	v_mul_f32_e32 v140, v33, v33
	v_mul_f32_e32 v141, v35, v35
	v_fmac_f32_e32 v140, v32, v32
	v_fmac_f32_e32 v141, v34, v34
	v_add_f32_e32 v140, v140, v141
	v_add_f32_e32 v142, v142, v140
	v_mov_b32_e32 v32, v142
	s_waitcnt vmcnt(16)
; __device__ __forceinline__ unsigned cvt_pk_bf16(float lo, float hi) { unsigned r; asm volatile("v_cvt_pk_bf16_f32 %0, %1, %2" : "=v"(r) : "v"(lo), "v"(hi)); return r; }
;     __device__ __forceinline__ void operator()(const f32x4 (&acc)[2][2][4][2], const Unit& u, int wr, int wc, int fr, int fq) const {
;     ...
;                     for (int n = 0; n < 2; ++n) { const size_t off = ro + bj * HALF + n * 16; const f32x4 hv = *(const f32x4*)(R + off) + acc[ai][bj][m][n];
;                         *(f32x4*)(H + off) = hv; ss += (hv[0] * hv[0] + hv[1] * hv[1]) + (hv[2] * hv[2] + hv[3] * hv[3]);
;                         if (WITH_A5) { const f32x4 gv = *(const f32x4*)(gm + col0 + bj * HALF + n * 16); u32x2 w; w.x = cvt_pk_bf16(hv[0] * gv[0], hv[1] * gv[1]); w.y = cvt_pk_bf16(hv[2] * gv[2], hv[3] * gv[3]); *(u32x2*)(a5 + off) = w; } }
;                 ss += __shfl_xor(ss, 16); ss += __shfl_xor(ss, 32);
;                 if (fq == 0) atomicAdd(rowss + row, ss); }
	v_pk_add_f32 v[28:29], v[28:29], v[174:175]
	v_pk_add_f32 v[30:31], v[30:31], v[176:177]
	v_pk_add_f32 v[24:25], v[24:25], v[178:179]
	v_pk_add_f32 v[26:27], v[26:27], v[180:181]
	v_pk_add_f32 v[20:21], v[20:21], v[182:183]
	v_pk_add_f32 v[22:23], v[22:23], v[184:185]
	v_pk_add_f32 v[16:17], v[16:17], v[186:187]
	v_pk_add_f32 v[18:19], v[18:19], v[188:189]
	global_store_dwordx4 v222, v[28:31], s[54:55]
	global_store_dwordx4 v222, v[24:27], s[54:55] offset:64
	global_store_dwordx4 v222, v[20:23], s[54:55] offset:512
	global_store_dwordx4 v222, v[16:19], s[54:55] offset:576
	s_add_u32 s54, s54, 0x20000
	s_addc_u32 s55, s55, 0
	v_mul_f32_e32 v140, v29, v29
	v_mul_f32_e32 v141, v31, v31
	v_fmac_f32_e32 v140, v28, v28
	v_fmac_f32_e32 v141, v30, v30
	v_add_f32_e32 v142, v140, v141
	v_mul_f32_e32 v140, v25, v25
	v_mul_f32_e32 v141, v27, v27
	v_fmac_f32_e32 v140, v24, v24
	v_fmac_f32_e32 v141, v26, v26
	v_add_f32_e32 v140, v140, v141
	v_add_f32_e32 v142, v142, v140
	v_mul_f32_e32 v140, v21, v21
	v_mul_f32_e32 v141, v23, v23
	v_fmac_f32_e32 v140, v20, v20
	v_fmac_f32_e32 v141, v22, v22
	v_add_f32_e32 v140, v140, v141
	v_add_f32_e32 v142, v142, v140
	v_mul_f32_e32 v140, v17, v17
	v_mul_f32_e32 v141, v19, v19
	v_fmac_f32_e32 v140, v16, v16
	v_fmac_f32_e32 v141, v18, v18
	v_add_f32_e32 v140, v140, v141
	v_add_f32_e32 v142, v142, v140
	v_mov_b32_e32 v16, v142
	s_waitcnt vmcnt(12)
	v_pk_add_f32 v[12:13], v[12:13], v[190:191]
	v_pk_add_f32 v[14:15], v[14:15], v[192:193]
	v_pk_add_f32 v[8:9], v[8:9], v[194:195]
	v_pk_add_f32 v[10:11], v[10:11], v[196:197]
	v_pk_add_f32 v[4:5], v[4:5], v[198:199]
	v_pk_add_f32 v[6:7], v[6:7], v[200:201]
	v_pk_add_f32 v[0:1], v[0:1], v[202:203]
	v_pk_add_f32 v[2:3], v[2:3], v[204:205]
	global_store_dwordx4 v222, v[12:15], s[54:55]
	global_store_dwordx4 v222, v[8:11], s[54:55] offset:64
	global_store_dwordx4 v222, v[4:7], s[54:55] offset:512
	global_store_dwordx4 v222, v[0:3], s[54:55] offset:576
	v_mul_f32_e32 v140, v13, v13
	v_mul_f32_e32 v141, v15, v15
	v_fmac_f32_e32 v140, v12, v12
	v_fmac_f32_e32 v141, v14, v14
	v_add_f32_e32 v142, v140, v141
	v_mul_f32_e32 v140, v9, v9
	v_mul_f32_e32 v141, v11, v11
	v_fmac_f32_e32 v140, v8, v8
	v_fmac_f32_e32 v141, v10, v10
	v_add_f32_e32 v140, v140, v141
	v_add_f32_e32 v142, v142, v140
	v_mul_f32_e32 v140, v5, v5
	v_mul_f32_e32 v141, v7, v7
	v_fmac_f32_e32 v140, v4, v4
	v_fmac_f32_e32 v141, v6, v6
	v_add_f32_e32 v140, v140, v141
	v_add_f32_e32 v142, v142, v140
	v_mul_f32_e32 v140, v1, v1
	v_mul_f32_e32 v141, v3, v3
	v_fmac_f32_e32 v140, v0, v0
	v_fmac_f32_e32 v141, v2, v2
	v_add_f32_e32 v140, v140, v141
	v_add_f32_e32 v142, v142, v140
	v_mov_b32_e32 v0, v142
	ds_bpermute_b32 v113, v151, v112
	ds_bpermute_b32 v97, v151, v96
	ds_bpermute_b32 v81, v151, v80
	ds_bpermute_b32 v65, v151, v64
	ds_bpermute_b32 v49, v151, v48
	ds_bpermute_b32 v33, v151, v32
	ds_bpermute_b32 v17, v151, v16
	ds_bpermute_b32 v1, v151, v0
	s_waitcnt lgkmcnt(0)
	v_add_f32_e32 v112, v112, v113
	v_add_f32_e32 v96, v96, v97
	v_add_f32_e32 v80, v80, v81
	v_add_f32_e32 v64, v64, v65
	v_add_f32_e32 v48, v48, v49
	v_add_f32_e32 v32, v32, v33
	v_add_f32_e32 v16, v16, v17
	v_add_f32_e32 v0, v0, v1
	ds_bpermute_b32 v113, v152, v112
	ds_bpermute_b32 v97, v152, v96
	ds_bpermute_b32 v81, v152, v80
	ds_bpermute_b32 v65, v152, v64
	ds_bpermute_b32 v49, v152, v48
	ds_bpermute_b32 v33, v152, v32
	ds_bpermute_b32 v17, v152, v16
	ds_bpermute_b32 v1, v152, v0
	s_waitcnt lgkmcnt(0)
	v_add_f32_e32 v112, v112, v113
	v_add_f32_e32 v96, v96, v97
	v_add_f32_e32 v80, v80, v81
	v_add_f32_e32 v64, v64, v65
	v_add_f32_e32 v48, v48, v49
	v_add_f32_e32 v32, v32, v33
	v_add_f32_e32 v16, v16, v17
	v_add_f32_e32 v0, v0, v1
	s_and_saveexec_b64 s[22:23], s[0:1]
	global_atomic_add_f32 v153, v112, s[58:59]
	global_atomic_add_f32 v153, v96, s[58:59] offset:64
	global_atomic_add_f32 v153, v80, s[58:59] offset:128
	global_atomic_add_f32 v153, v64, s[58:59] offset:192
	global_atomic_add_f32 v153, v48, s[58:59] offset:512
	global_atomic_add_f32 v153, v32, s[58:59] offset:576
	global_atomic_add_f32 v153, v16, s[58:59] offset:640
	global_atomic_add_f32 v153, v0, s[58:59] offset:704
	s_or_b64 exec, exec, s[22:23]
	s_andn2_b64 vcc, exec, s[4:5]
	s_mov_b64 s[4:5], -1
	s_cbranch_vccnz .LBB0_893
	s_andn2_b64 vcc, exec, s[8:9]
	s_cbranch_vccnz .LBB0_892
	s_barrier
	s_branch .LBB0_892
